# v21 + final RMSNorm output stores (now full 1 KiB lines per instruction) issued write-through, so no dirty L2 lines remain at kernel end
# speedup vs baseline: 1.0022x; 1.0022x over previous
; __device__ __forceinline__ float ss_val(u64 v) { return (float)v * (1.0f / 1099511627776.0f); }
; __global__ void __launch_bounds__(NTHREADS, 2) fwd(Args a) {
;     ...
;             for (int r2 = 0; r2 < 2; ++r2) {
;                 if (r2 == 1 && !two) break;
;                 const float rs = __builtin_amdgcn_rsqf(ss_val(sv[r2]) * (1.f / D) + EPS);
;                 f32x4* orow = (f32x4*)(outb + (size_t)(r2 ? m1 : m) * D);
; #pragma unroll
;                 for (int j = 0; j < 2; ++j) {
;                     const u32x4 x4 = xv[r2][j]; const f32x4 w0 = wv[j][0], w1 = wv[j][1];
;                     f32x4 o0, o1;
;                     o0[0] = bf_lo(x4[0]) * rs * w0[0]; o0[1] = bf_hi(x4[0]) * rs * w0[1]; o0[2] = bf_lo(x4[1]) * rs * w0[2]; o0[3] = bf_hi(x4[1]) * rs * w0[3];
;                     o1[0] = bf_lo(x4[2]) * rs * w1[0]; o1[1] = bf_hi(x4[2]) * rs * w1[1]; o1[2] = bf_lo(x4[3]) * rs * w1[2]; o1[3] = bf_hi(x4[3]) * rs * w1[3];
;                     orow[2 * (lane + 64 * j)] = o0; orow[2 * (lane + 64 * j) + 1] = o1;
;                 }
;             }
;         }
.Lfn_a_p:
	s_lshl_b32 s18, s38, 12
	s_add_u32 s18, s4, s18
	s_addc_u32 s19, s5, 0
	v_cvt_f32_u32_e32 v66, v24
	v_cvt_f32_u32_e32 v67, v25
	v_fmamk_f32 v66, v67, 0x4f800000, v66
	v_fmamk_f32 v66, v66, 0x26800000, v4
	v_rsq_f32_e32 v64, v66
	v_lshlrev_b32_e32 v60, 16, v26
	v_and_b32_e32 v61, 0xffff0000, v26
	v_lshlrev_b32_e32 v62, 16, v27
	v_and_b32_e32 v63, 0xffff0000, v27
	v_pk_mul_f32 v[60:61], v[64:65], v[60:61] op_sel_hi:[0,1]
	v_pk_mul_f32 v[62:63], v[64:65], v[62:63] op_sel_hi:[0,1]
	v_pk_mul_f32 v[68:69], v[8:9], v[60:61]
	v_pk_mul_f32 v[70:71], v[10:11], v[62:63]
	global_store_dwordx4 v3, v[68:71], s[18:19] offset:0 sc0 sc1
	v_lshlrev_b32_e32 v60, 16, v28
	v_and_b32_e32 v61, 0xffff0000, v28
	v_lshlrev_b32_e32 v62, 16, v29
	v_and_b32_e32 v63, 0xffff0000, v29
	v_pk_mul_f32 v[60:61], v[64:65], v[60:61] op_sel_hi:[0,1]
	v_pk_mul_f32 v[62:63], v[64:65], v[62:63] op_sel_hi:[0,1]
	v_pk_mul_f32 v[72:73], v[12:13], v[60:61]
	v_pk_mul_f32 v[74:75], v[14:15], v[62:63]
	global_store_dwordx4 v3, v[72:75], s[18:19] offset:1024 sc0 sc1
	v_lshlrev_b32_e32 v60, 16, v30
	v_and_b32_e32 v61, 0xffff0000, v30
	v_lshlrev_b32_e32 v62, 16, v31
	v_and_b32_e32 v63, 0xffff0000, v31
	v_pk_mul_f32 v[60:61], v[64:65], v[60:61] op_sel_hi:[0,1]
	v_pk_mul_f32 v[62:63], v[64:65], v[62:63] op_sel_hi:[0,1]
	v_pk_mul_f32 v[76:77], v[16:17], v[60:61]
	v_pk_mul_f32 v[78:79], v[18:19], v[62:63]
	global_store_dwordx4 v3, v[76:79], s[18:19] offset:2048 sc0 sc1
	v_lshlrev_b32_e32 v60, 16, v32
	v_and_b32_e32 v61, 0xffff0000, v32
	v_lshlrev_b32_e32 v62, 16, v33
	v_and_b32_e32 v63, 0xffff0000, v33
	v_pk_mul_f32 v[60:61], v[64:65], v[60:61] op_sel_hi:[0,1]
	v_pk_mul_f32 v[62:63], v[64:65], v[62:63] op_sel_hi:[0,1]
	v_pk_mul_f32 v[80:81], v[20:21], v[60:61]
	v_pk_mul_f32 v[82:83], v[22:23], v[62:63]
	global_store_dwordx4 v3, v[80:83], s[18:19] offset:3072 sc0 sc1
	s_add_u32 s38, s38, s36
	s_cmp_lt_u32 s38, 0x1000
	s_cbranch_scc0 .LBB0_1445

; __device__ __forceinline__ float ss_val(u64 v) { return (float)v * (1.0f / 1099511627776.0f); }
; __global__ void __launch_bounds__(NTHREADS, 2) fwd(Args a) {
;     ...
;             for (int r2 = 0; r2 < 2; ++r2) {
;                 if (r2 == 1 && !two) break;
;                 const float rs = __builtin_amdgcn_rsqf(ss_val(sv[r2]) * (1.f / D) + EPS);
;                 f32x4* orow = (f32x4*)(outb + (size_t)(r2 ? m1 : m) * D);
; #pragma unroll
;                 for (int j = 0; j < 2; ++j) {
;                     const u32x4 x4 = xv[r2][j]; const f32x4 w0 = wv[j][0], w1 = wv[j][1];
;                     f32x4 o0, o1;
;                     o0[0] = bf_lo(x4[0]) * rs * w0[0]; o0[1] = bf_hi(x4[0]) * rs * w0[1]; o0[2] = bf_lo(x4[1]) * rs * w0[2]; o0[3] = bf_hi(x4[1]) * rs * w0[3];
;                     o1[0] = bf_lo(x4[2]) * rs * w1[0]; o1[1] = bf_hi(x4[2]) * rs * w1[1]; o1[2] = bf_lo(x4[3]) * rs * w1[2]; o1[3] = bf_hi(x4[3]) * rs * w1[3];
;                     orow[2 * (lane + 64 * j)] = o0; orow[2 * (lane + 64 * j) + 1] = o1;
;                 }
;             }
.Lfn_b_p:
	s_lshl_b32 s18, s38, 12
	s_add_u32 s18, s4, s18
	s_addc_u32 s19, s5, 0
	v_cvt_f32_u32_e32 v66, v36
	v_cvt_f32_u32_e32 v67, v37
	v_fmamk_f32 v66, v67, 0x4f800000, v66
	v_fmamk_f32 v66, v66, 0x26800000, v4
	v_rsq_f32_e32 v64, v66
	v_lshlrev_b32_e32 v60, 16, v38
	v_and_b32_e32 v61, 0xffff0000, v38
	v_lshlrev_b32_e32 v62, 16, v39
	v_and_b32_e32 v63, 0xffff0000, v39
	v_pk_mul_f32 v[60:61], v[64:65], v[60:61] op_sel_hi:[0,1]
	v_pk_mul_f32 v[62:63], v[64:65], v[62:63] op_sel_hi:[0,1]
	v_pk_mul_f32 v[68:69], v[8:9], v[60:61]
	v_pk_mul_f32 v[70:71], v[10:11], v[62:63]
	global_store_dwordx4 v3, v[68:71], s[18:19] offset:0 sc0 sc1
	v_lshlrev_b32_e32 v60, 16, v40
	v_and_b32_e32 v61, 0xffff0000, v40
	v_lshlrev_b32_e32 v62, 16, v41
	v_and_b32_e32 v63, 0xffff0000, v41
	v_pk_mul_f32 v[60:61], v[64:65], v[60:61] op_sel_hi:[0,1]
	v_pk_mul_f32 v[62:63], v[64:65], v[62:63] op_sel_hi:[0,1]
	v_pk_mul_f32 v[72:73], v[12:13], v[60:61]
	v_pk_mul_f32 v[74:75], v[14:15], v[62:63]
	global_store_dwordx4 v3, v[72:75], s[18:19] offset:1024 sc0 sc1
	v_lshlrev_b32_e32 v60, 16, v42
	v_and_b32_e32 v61, 0xffff0000, v42
	v_lshlrev_b32_e32 v62, 16, v43
	v_and_b32_e32 v63, 0xffff0000, v43
	v_pk_mul_f32 v[60:61], v[64:65], v[60:61] op_sel_hi:[0,1]
	v_pk_mul_f32 v[62:63], v[64:65], v[62:63] op_sel_hi:[0,1]
	v_pk_mul_f32 v[76:77], v[16:17], v[60:61]
	v_pk_mul_f32 v[78:79], v[18:19], v[62:63]
	global_store_dwordx4 v3, v[76:79], s[18:19] offset:2048 sc0 sc1
	v_lshlrev_b32_e32 v60, 16, v44
	v_and_b32_e32 v61, 0xffff0000, v44
	v_lshlrev_b32_e32 v62, 16, v45
	v_and_b32_e32 v63, 0xffff0000, v45
	v_pk_mul_f32 v[60:61], v[64:65], v[60:61] op_sel_hi:[0,1]
	v_pk_mul_f32 v[62:63], v[64:65], v[62:63] op_sel_hi:[0,1]
	v_pk_mul_f32 v[80:81], v[20:21], v[60:61]
	v_pk_mul_f32 v[82:83], v[22:23], v[62:63]
	global_store_dwordx4 v3, v[80:83], s[18:19] offset:3072 sc0 sc1
	s_add_u32 s38, s38, s36
	s_cmp_lt_u32 s38, 0x1000
	s_cbranch_scc0 .LBB0_1445

; __device__ __forceinline__ float ss_val(u64 v) { return (float)v * (1.0f / 1099511627776.0f); }
; __global__ void __launch_bounds__(NTHREADS, 2) fwd(Args a) {
;     ...
;             for (int r2 = 0; r2 < 2; ++r2) {
;                 if (r2 == 1 && !two) break;
;                 const float rs = __builtin_amdgcn_rsqf(ss_val(sv[r2]) * (1.f / D) + EPS);
;                 f32x4* orow = (f32x4*)(outb + (size_t)(r2 ? m1 : m) * D);
; #pragma unroll
;                 for (int j = 0; j < 2; ++j) {
;                     const u32x4 x4 = xv[r2][j]; const f32x4 w0 = wv[j][0], w1 = wv[j][1];
;                     f32x4 o0, o1;
;                     o0[0] = bf_lo(x4[0]) * rs * w0[0]; o0[1] = bf_hi(x4[0]) * rs * w0[1]; o0[2] = bf_lo(x4[1]) * rs * w0[2]; o0[3] = bf_hi(x4[1]) * rs * w0[3];
;                     o1[0] = bf_lo(x4[2]) * rs * w1[0]; o1[1] = bf_hi(x4[2]) * rs * w1[1]; o1[2] = bf_lo(x4[3]) * rs * w1[2]; o1[3] = bf_hi(x4[3]) * rs * w1[3];
;                     orow[2 * (lane + 64 * j)] = o0; orow[2 * (lane + 64 * j) + 1] = o1;
;                 }
;             }
.Lfn_c_p:
	s_lshl_b32 s18, s38, 12
	s_add_u32 s18, s4, s18
	s_addc_u32 s19, s5, 0
	v_cvt_f32_u32_e32 v66, v48
	v_cvt_f32_u32_e32 v67, v49
	v_fmamk_f32 v66, v67, 0x4f800000, v66
	v_fmamk_f32 v66, v66, 0x26800000, v4
	v_rsq_f32_e32 v64, v66
	v_lshlrev_b32_e32 v60, 16, v50
	v_and_b32_e32 v61, 0xffff0000, v50
	v_lshlrev_b32_e32 v62, 16, v51
	v_and_b32_e32 v63, 0xffff0000, v51
	v_pk_mul_f32 v[60:61], v[64:65], v[60:61] op_sel_hi:[0,1]
	v_pk_mul_f32 v[62:63], v[64:65], v[62:63] op_sel_hi:[0,1]
	v_pk_mul_f32 v[68:69], v[8:9], v[60:61]
	v_pk_mul_f32 v[70:71], v[10:11], v[62:63]
	global_store_dwordx4 v3, v[68:71], s[18:19] offset:0 sc0 sc1
	v_lshlrev_b32_e32 v60, 16, v52
	v_and_b32_e32 v61, 0xffff0000, v52
	v_lshlrev_b32_e32 v62, 16, v53
	v_and_b32_e32 v63, 0xffff0000, v53
	v_pk_mul_f32 v[60:61], v[64:65], v[60:61] op_sel_hi:[0,1]
	v_pk_mul_f32 v[62:63], v[64:65], v[62:63] op_sel_hi:[0,1]
	v_pk_mul_f32 v[72:73], v[12:13], v[60:61]
	v_pk_mul_f32 v[74:75], v[14:15], v[62:63]
	global_store_dwordx4 v3, v[72:75], s[18:19] offset:1024 sc0 sc1
	v_lshlrev_b32_e32 v60, 16, v54
	v_and_b32_e32 v61, 0xffff0000, v54
	v_lshlrev_b32_e32 v62, 16, v55
	v_and_b32_e32 v63, 0xffff0000, v55
	v_pk_mul_f32 v[60:61], v[64:65], v[60:61] op_sel_hi:[0,1]
	v_pk_mul_f32 v[62:63], v[64:65], v[62:63] op_sel_hi:[0,1]
	v_pk_mul_f32 v[76:77], v[16:17], v[60:61]
	v_pk_mul_f32 v[78:79], v[18:19], v[62:63]
	global_store_dwordx4 v3, v[76:79], s[18:19] offset:2048 sc0 sc1
	v_lshlrev_b32_e32 v60, 16, v56
	v_and_b32_e32 v61, 0xffff0000, v56
	v_lshlrev_b32_e32 v62, 16, v57
	v_and_b32_e32 v63, 0xffff0000, v57
	v_pk_mul_f32 v[60:61], v[64:65], v[60:61] op_sel_hi:[0,1]
	v_pk_mul_f32 v[62:63], v[64:65], v[62:63] op_sel_hi:[0,1]
	v_pk_mul_f32 v[80:81], v[20:21], v[60:61]
	v_pk_mul_f32 v[82:83], v[22:23], v[62:63]
	global_store_dwordx4 v3, v[80:83], s[18:19] offset:3072 sc0 sc1
	s_add_u32 s38, s38, s36
	s_cmp_lt_u32 s38, 0x1000
	s_cbranch_scc0 .LBB0_1445

; __device__ __forceinline__ float ss_val(u64 v) { return (float)v * (1.0f / 1099511627776.0f); }
; __global__ void __launch_bounds__(NTHREADS, 2) fwd(Args a) {
;     ...
;             for (int r2 = 0; r2 < 2; ++r2) {
;                 if (r2 == 1 && !two) break;
;                 const float rs = __builtin_amdgcn_rsqf(ss_val(sv[r2]) * (1.f / D) + EPS);
;                 f32x4* orow = (f32x4*)(outb + (size_t)(r2 ? m1 : m) * D);
; #pragma unroll
;                 for (int j = 0; j < 2; ++j) {
;                     const u32x4 x4 = xv[r2][j]; const f32x4 w0 = wv[j][0], w1 = wv[j][1];
;                     f32x4 o0, o1;
;                     o0[0] = bf_lo(x4[0]) * rs * w0[0]; o0[1] = bf_hi(x4[0]) * rs * w0[1]; o0[2] = bf_lo(x4[1]) * rs * w0[2]; o0[3] = bf_hi(x4[1]) * rs * w0[3];
;                     o1[0] = bf_lo(x4[2]) * rs * w1[0]; o1[1] = bf_hi(x4[2]) * rs * w1[1]; o1[2] = bf_lo(x4[3]) * rs * w1[2]; o1[3] = bf_hi(x4[3]) * rs * w1[3];
;                     orow[2 * (lane + 64 * j)] = o0; orow[2 * (lane + 64 * j) + 1] = o1;
;                 }
;             }
.Lfn_e_p:
	s_lshl_b32 s18, s38, 12
	s_add_u32 s18, s4, s18
	s_addc_u32 s19, s5, 0
	v_cvt_f32_u32_e32 v66, v36
	v_cvt_f32_u32_e32 v67, v37
	v_fmamk_f32 v66, v67, 0x4f800000, v66
	v_fmamk_f32 v66, v66, 0x26800000, v4
	v_rsq_f32_e32 v64, v66
	v_lshlrev_b32_e32 v60, 16, v38
	v_and_b32_e32 v61, 0xffff0000, v38
	v_lshlrev_b32_e32 v62, 16, v39
	v_and_b32_e32 v63, 0xffff0000, v39
	v_pk_mul_f32 v[60:61], v[64:65], v[60:61] op_sel_hi:[0,1]
	v_pk_mul_f32 v[62:63], v[64:65], v[62:63] op_sel_hi:[0,1]
	v_pk_mul_f32 v[68:69], v[8:9], v[60:61]
	v_pk_mul_f32 v[70:71], v[10:11], v[62:63]
	global_store_dwordx4 v3, v[68:71], s[18:19] offset:0 sc0 sc1
	v_lshlrev_b32_e32 v60, 16, v40
	v_and_b32_e32 v61, 0xffff0000, v40
	v_lshlrev_b32_e32 v62, 16, v41
	v_and_b32_e32 v63, 0xffff0000, v41
	v_pk_mul_f32 v[60:61], v[64:65], v[60:61] op_sel_hi:[0,1]
	v_pk_mul_f32 v[62:63], v[64:65], v[62:63] op_sel_hi:[0,1]
	v_pk_mul_f32 v[72:73], v[12:13], v[60:61]
	v_pk_mul_f32 v[74:75], v[14:15], v[62:63]
	global_store_dwordx4 v3, v[72:75], s[18:19] offset:1024 sc0 sc1
	v_lshlrev_b32_e32 v60, 16, v42
	v_and_b32_e32 v61, 0xffff0000, v42
	v_lshlrev_b32_e32 v62, 16, v43
	v_and_b32_e32 v63, 0xffff0000, v43
	v_pk_mul_f32 v[60:61], v[64:65], v[60:61] op_sel_hi:[0,1]
	v_pk_mul_f32 v[62:63], v[64:65], v[62:63] op_sel_hi:[0,1]
	v_pk_mul_f32 v[76:77], v[16:17], v[60:61]
	v_pk_mul_f32 v[78:79], v[18:19], v[62:63]
	global_store_dwordx4 v3, v[76:79], s[18:19] offset:2048 sc0 sc1
	v_lshlrev_b32_e32 v60, 16, v44
	v_and_b32_e32 v61, 0xffff0000, v44
	v_lshlrev_b32_e32 v62, 16, v45
	v_and_b32_e32 v63, 0xffff0000, v45
	v_pk_mul_f32 v[60:61], v[64:65], v[60:61] op_sel_hi:[0,1]
	v_pk_mul_f32 v[62:63], v[64:65], v[62:63] op_sel_hi:[0,1]
	v_pk_mul_f32 v[80:81], v[20:21], v[60:61]
	v_pk_mul_f32 v[82:83], v[22:23], v[62:63]
	global_store_dwordx4 v3, v[80:83], s[18:19] offset:3072 sc0 sc1
	s_add_u32 s38, s38, s36
	s_cmp_lt_u32 s38, 0x1000
	s_cbranch_scc0 .LBB0_1445
	s_branch .Lfn_c
